# ret_state scan step: 64 exec-mask diamonds around the transpose reads replaced by straight-line reads (wave-uniform select folded into base address), two K-steps in flight
# baseline (speedup 1.0000x reference)
.LBB0_710:
	s_and_saveexec_b64 s[18:19], s[8:9]
	s_cbranch_execz .LBB0_707
	v_add_u32_e32 v236, 0x200, v43
	v_add_u32_e32 v237, 0x200, v44
	v_cndmask_b32_e64 v236, v43, v236, s[10:11]
	v_cndmask_b32_e64 v237, v44, v237, s[12:13]
	ds_read_b64_tr_b16 v[26:27], v236
	ds_read_b64_tr_b16 v[28:29], v236 offset:1024
	ds_read_b64_tr_b16 v[30:31], v237
	ds_read_b64_tr_b16 v[32:33], v237 offset:1024
	ds_read_b64_tr_b16 v[238:239], v236 offset:2048
	ds_read_b64_tr_b16 v[240:241], v236 offset:3072
	ds_read_b64_tr_b16 v[242:243], v237 offset:2048
	ds_read_b64_tr_b16 v[244:245], v237 offset:3072
	v_mov_b32_e32 v35, v34
	v_pk_mul_f32 v[16:17], v[34:35], v[16:17]
	v_pk_mul_f32 v[14:15], v[34:35], v[14:15]
	v_pk_mul_f32 v[12:13], v[34:35], v[12:13]
	v_pk_mul_f32 v[10:11], v[34:35], v[10:11]
	v_pk_mul_f32 v[8:9], v[34:35], v[8:9]
	v_pk_mul_f32 v[6:7], v[34:35], v[6:7]
	v_pk_mul_f32 v[4:5], v[34:35], v[4:5]
	v_pk_mul_f32 v[2:3], v[40:41], v[2:3]
	s_waitcnt lgkmcnt(4)
	s_nop 1
	v_mfma_f32_32x32x16_bf16 v[2:17], v[26:29], v[30:33], v[2:17]
	ds_read_b64_tr_b16 v[26:27], v236 offset:4096
	ds_read_b64_tr_b16 v[28:29], v236 offset:5120
	ds_read_b64_tr_b16 v[30:31], v237 offset:4096
	ds_read_b64_tr_b16 v[32:33], v237 offset:5120
	s_waitcnt lgkmcnt(4)
	v_mfma_f32_32x32x16_bf16 v[2:17], v[238:241], v[242:245], v[2:17]
	ds_read_b64_tr_b16 v[238:239], v236 offset:6144
	ds_read_b64_tr_b16 v[240:241], v236 offset:7168
	ds_read_b64_tr_b16 v[242:243], v237 offset:6144
	ds_read_b64_tr_b16 v[244:245], v237 offset:7168
	s_waitcnt lgkmcnt(4)
	v_mfma_f32_32x32x16_bf16 v[2:17], v[26:29], v[30:33], v[2:17]
	s_waitcnt lgkmcnt(0)
	v_mfma_f32_32x32x16_bf16 v[2:17], v[238:241], v[242:245], v[2:17]
	s_mov_b64 s[20:21], -1
	s_and_b64 vcc, exec, s[6:7]
	s_cbranch_vccz .LBB0_780
	s_cmp_eq_u32 s24, 3
	s_mov_b32 s36, 7
	s_cbranch_scc1 .LBB0_778
	s_cmp_gt_u32 s24, 3
	s_cselect_b64 s[20:21], -1, 0
	s_and_b32 s24, s25, 3
	s_cmp_eq_u32 s24, 0
	s_cselect_b64 s[62:63], -1, 0
	s_lshr_b32 s24, s25, 2
	s_add_i32 s24, s24, -1
	s_and_b64 s[20:21], s[20:21], s[62:63]
	s_and_b64 s[20:21], s[20:21], exec
	s_cselect_b32 s36, s24, -1
